# y2 transpose phase: four tile loads in flight per workgroup (counted vmcnt, unrolled) instead of one
# speedup vs baseline: 1.0050x; 1.0050x over previous
.LBB0_2128:
	s_cmp_gt_i32 s40, 14
	s_cselect_b64 s[4:5], -1, 0
	s_cmp_lt_i32 s41, 15
	s_cselect_b64 s[6:7], -1, 0
	s_or_b64 s[4:5], s[4:5], s[6:7]
	s_and_b64 vcc, exec, s[4:5]
	s_cbranch_vccnz .LBB0_2186
	s_mov_b64 s[4:5], s[0:1]
	s_cmpk_gt_i32 s2, 0x1fff
	s_cbranch_scc1 .LBB0_2136
	s_load_dwordx2 s[4:5], s[4:5], 0x1e8
	v_mbcnt_lo_u32_b32 v0, -1, 0
	v_mbcnt_hi_u32_b32 v0, -1, v0
	v_add_u32_e32 v1, s63, v0
	v_lshlrev_b32_e32 v0, 3, v0
	s_waitcnt lgkmcnt(0)
	s_add_u32 s6, s4, 0x4000000
	s_addc_u32 s7, s5, 0
	s_lshl_b32 s3, s2, 6
	v_ashrrev_i32_e32 v6, 3, v1
	s_and_b32 s8, s3, 0x7c0
	v_and_b32_e32 v10, 56, v0
	v_add_u32_e32 v0, s8, v6
	v_ashrrev_i32_e32 v1, 31, v0
	s_lshl_b32 s8, s2, 1
	v_lshlrev_b64 v[0:1], 15, v[0:1]
	s_and_b32 s10, s8, 0xffffffc0
	v_lshl_add_u64 v[0:1], s[4:5], 0, v[0:1]
	s_ashr_i32 s11, s10, 31
	v_mov_b32_e32 v5, 0
	v_lshlrev_b32_e32 v4, 1, v10
	v_lshl_add_u64 v[0:1], s[10:11], 1, v[0:1]
	v_lshl_add_u64 v[0:1], v[0:1], 0, v[4:5]
	global_load_dwordx4 v[0:3], v[0:1], off
	s_load_dword s14, s[0:1], 0x230
	s_movk_i32 s10, 0x90
	v_add_u32_e32 v4, 0, v4
	v_mul_lo_u32 v7, v6, s10
	v_lshl_add_u32 v8, v6, 1, 0
	v_mul_u32_u24_e32 v9, 0x90, v10
	s_mov_b32 s9, 0
	s_waitcnt lgkmcnt(0)
	s_lshl_b32 s15, s14, 6
	s_lshl_b32 s16, s14, 1
	v_add_u32_e32 v7, v4, v7
	v_add_u32_e32 v8, v8, v9
	s_mov_b32 s17, 0x5040100
	v_lshlrev_b32_e32 v4, 1, v10
	s_mov_b32 s18, s2
	s_cmp_eq_u32 s14, 0x100
	s_cbranch_scc1 .Ltrp_fast
	s_branch .LBB0_2132
.Ltrp_fast:
	s_lshl_b32 s64, s2, 6
	s_and_b32 s64, s64, 0x7c0
	s_mov_b32 s65, 0
	s_lshl_b32 s66, s2, 1
	s_and_b32 s66, s66, 0xffffffc0
	s_mov_b32 s67, 0
	s_mov_b32 s68, 0x200000
	s_mov_b32 s69, 0
	s_movk_i32 s70, 0x400
	s_mov_b32 s71, 0
	v_add_u32_e32 v48, s64, v6
	v_mov_b32_e32 v49, 0
	v_lshlrev_b64 v[48:49], 15, v[48:49]
	v_lshl_add_u64 v[48:49], s[4:5], 0, v[48:49]
	v_lshl_add_u64 v[48:49], s[66:67], 1, v[48:49]
	v_lshl_add_u64 v[48:49], v[48:49], 0, v[4:5]
	v_add_u32_e32 v50, s66, v6
	v_mov_b32_e32 v51, 0
	v_lshlrev_b64 v[50:51], 12, v[50:51]
	v_lshl_add_u64 v[50:51], s[6:7], 0, v[50:51]
	v_lshl_add_u64 v[50:51], s[64:65], 1, v[50:51]
	v_lshl_add_u64 v[50:51], v[50:51], 0, v[4:5]
	v_lshl_add_u64 v[48:49], v[48:49], 0, s[70:71]
	global_load_dwordx4 v[32:35], v[48:49], off
	v_lshl_add_u64 v[48:49], v[48:49], 0, s[70:71]
	global_load_dwordx4 v[36:39], v[48:49], off
	v_lshl_add_u64 v[48:49], v[48:49], 0, s[70:71]
	global_load_dwordx4 v[40:43], v[48:49], off
	s_waitcnt vmcnt(3)
	ds_write_b128 v7, v[0:3]
	v_lshl_add_u64 v[48:49], v[48:49], 0, s[70:71]
	global_load_dwordx4 v[0:3], v[48:49], off
	s_waitcnt lgkmcnt(0)
	s_barrier
	ds_read_u16 v9, v8 offset:288
	ds_read_u16 v10, v8 offset:432
	ds_read_u16 v11, v8 offset:576
	ds_read_u16 v12, v8 offset:864
	ds_read_u16 v13, v8 offset:1008
	ds_read_u16 v14, v8 offset:720
	ds_read_u16 v15, v8
	ds_read_u16 v16, v8 offset:144
	s_waitcnt lgkmcnt(3)
	v_perm_b32 v13, v13, v12, s17
	s_waitcnt lgkmcnt(2)
	v_perm_b32 v12, v14, v11, s17
	v_perm_b32 v11, v10, v9, s17
	s_waitcnt lgkmcnt(0)
	v_perm_b32 v10, v16, v15, s17
	global_store_dwordx4 v[50:51], v[10:13], off
	v_lshl_add_u64 v[50:51], v[50:51], 0, s[68:69]
	s_barrier
	s_waitcnt vmcnt(4)
	ds_write_b128 v7, v[32:35]
	v_lshl_add_u64 v[48:49], v[48:49], 0, s[70:71]
	global_load_dwordx4 v[32:35], v[48:49], off
	s_waitcnt lgkmcnt(0)
	s_barrier
	ds_read_u16 v9, v8 offset:288
	ds_read_u16 v10, v8 offset:432
	ds_read_u16 v11, v8 offset:576
	ds_read_u16 v12, v8 offset:864
	ds_read_u16 v13, v8 offset:1008
	ds_read_u16 v14, v8 offset:720
	ds_read_u16 v15, v8
	ds_read_u16 v16, v8 offset:144
	s_waitcnt lgkmcnt(3)
	v_perm_b32 v13, v13, v12, s17
	s_waitcnt lgkmcnt(2)
	v_perm_b32 v12, v14, v11, s17
	v_perm_b32 v11, v10, v9, s17
	s_waitcnt lgkmcnt(0)
	v_perm_b32 v10, v16, v15, s17
	global_store_dwordx4 v[50:51], v[10:13], off
	v_lshl_add_u64 v[50:51], v[50:51], 0, s[68:69]
	s_barrier
	s_waitcnt vmcnt(5)
	ds_write_b128 v7, v[36:39]
	v_lshl_add_u64 v[48:49], v[48:49], 0, s[70:71]
	global_load_dwordx4 v[36:39], v[48:49], off
	s_waitcnt lgkmcnt(0)
	s_barrier
	ds_read_u16 v9, v8 offset:288
	ds_read_u16 v10, v8 offset:432
	ds_read_u16 v11, v8 offset:576
	ds_read_u16 v12, v8 offset:864
	ds_read_u16 v13, v8 offset:1008
	ds_read_u16 v14, v8 offset:720
	ds_read_u16 v15, v8
	ds_read_u16 v16, v8 offset:144
	s_waitcnt lgkmcnt(3)
	v_perm_b32 v13, v13, v12, s17
	s_waitcnt lgkmcnt(2)
	v_perm_b32 v12, v14, v11, s17
	v_perm_b32 v11, v10, v9, s17
	s_waitcnt lgkmcnt(0)
	v_perm_b32 v10, v16, v15, s17
	global_store_dwordx4 v[50:51], v[10:13], off
	v_lshl_add_u64 v[50:51], v[50:51], 0, s[68:69]
	s_barrier
	s_waitcnt vmcnt(6)
	ds_write_b128 v7, v[40:43]
	v_lshl_add_u64 v[48:49], v[48:49], 0, s[70:71]
	global_load_dwordx4 v[40:43], v[48:49], off
	s_waitcnt lgkmcnt(0)
	s_barrier
	ds_read_u16 v9, v8 offset:288
	ds_read_u16 v10, v8 offset:432
	ds_read_u16 v11, v8 offset:576
	ds_read_u16 v12, v8 offset:864
	ds_read_u16 v13, v8 offset:1008
	ds_read_u16 v14, v8 offset:720
	ds_read_u16 v15, v8
	ds_read_u16 v16, v8 offset:144
	s_waitcnt lgkmcnt(3)
	v_perm_b32 v13, v13, v12, s17
	s_waitcnt lgkmcnt(2)
	v_perm_b32 v12, v14, v11, s17
	v_perm_b32 v11, v10, v9, s17
	s_waitcnt lgkmcnt(0)
	v_perm_b32 v10, v16, v15, s17
	global_store_dwordx4 v[50:51], v[10:13], off
	v_lshl_add_u64 v[50:51], v[50:51], 0, s[68:69]
	s_barrier
	s_waitcnt vmcnt(7)
	ds_write_b128 v7, v[0:3]
	v_lshl_add_u64 v[48:49], v[48:49], 0, s[70:71]
	global_load_dwordx4 v[0:3], v[48:49], off
	s_waitcnt lgkmcnt(0)
	s_barrier
	ds_read_u16 v9, v8 offset:288
	ds_read_u16 v10, v8 offset:432
	ds_read_u16 v11, v8 offset:576
	ds_read_u16 v12, v8 offset:864
	ds_read_u16 v13, v8 offset:1008
	ds_read_u16 v14, v8 offset:720
	ds_read_u16 v15, v8
	ds_read_u16 v16, v8 offset:144
	s_waitcnt lgkmcnt(3)
	v_perm_b32 v13, v13, v12, s17
	s_waitcnt lgkmcnt(2)
	v_perm_b32 v12, v14, v11, s17
	v_perm_b32 v11, v10, v9, s17
	s_waitcnt lgkmcnt(0)
	v_perm_b32 v10, v16, v15, s17
	global_store_dwordx4 v[50:51], v[10:13], off
	v_lshl_add_u64 v[50:51], v[50:51], 0, s[68:69]
	s_barrier
	s_waitcnt vmcnt(7)
	ds_write_b128 v7, v[32:35]
	v_lshl_add_u64 v[48:49], v[48:49], 0, s[70:71]
	global_load_dwordx4 v[32:35], v[48:49], off
	s_waitcnt lgkmcnt(0)
	s_barrier
	ds_read_u16 v9, v8 offset:288
	ds_read_u16 v10, v8 offset:432
	ds_read_u16 v11, v8 offset:576
	ds_read_u16 v12, v8 offset:864
	ds_read_u16 v13, v8 offset:1008
	ds_read_u16 v14, v8 offset:720
	ds_read_u16 v15, v8
	ds_read_u16 v16, v8 offset:144
	s_waitcnt lgkmcnt(3)
	v_perm_b32 v13, v13, v12, s17
	s_waitcnt lgkmcnt(2)
	v_perm_b32 v12, v14, v11, s17
	v_perm_b32 v11, v10, v9, s17
	s_waitcnt lgkmcnt(0)
	v_perm_b32 v10, v16, v15, s17
	global_store_dwordx4 v[50:51], v[10:13], off
	v_lshl_add_u64 v[50:51], v[50:51], 0, s[68:69]
	s_barrier
	s_waitcnt vmcnt(7)
	ds_write_b128 v7, v[36:39]
	v_lshl_add_u64 v[48:49], v[48:49], 0, s[70:71]
	global_load_dwordx4 v[36:39], v[48:49], off
	s_waitcnt lgkmcnt(0)
	s_barrier
	ds_read_u16 v9, v8 offset:288
	ds_read_u16 v10, v8 offset:432
	ds_read_u16 v11, v8 offset:576
	ds_read_u16 v12, v8 offset:864
	ds_read_u16 v13, v8 offset:1008
	ds_read_u16 v14, v8 offset:720
	ds_read_u16 v15, v8
	ds_read_u16 v16, v8 offset:144
	s_waitcnt lgkmcnt(3)
	v_perm_b32 v13, v13, v12, s17
	s_waitcnt lgkmcnt(2)
	v_perm_b32 v12, v14, v11, s17
	v_perm_b32 v11, v10, v9, s17
	s_waitcnt lgkmcnt(0)
	v_perm_b32 v10, v16, v15, s17
	global_store_dwordx4 v[50:51], v[10:13], off
	v_lshl_add_u64 v[50:51], v[50:51], 0, s[68:69]
	s_barrier
	s_waitcnt vmcnt(7)
	ds_write_b128 v7, v[40:43]
	v_lshl_add_u64 v[48:49], v[48:49], 0, s[70:71]
	global_load_dwordx4 v[40:43], v[48:49], off
	s_waitcnt lgkmcnt(0)
	s_barrier
	ds_read_u16 v9, v8 offset:288
	ds_read_u16 v10, v8 offset:432
	ds_read_u16 v11, v8 offset:576
	ds_read_u16 v12, v8 offset:864
	ds_read_u16 v13, v8 offset:1008
	ds_read_u16 v14, v8 offset:720
	ds_read_u16 v15, v8
	ds_read_u16 v16, v8 offset:144
	s_waitcnt lgkmcnt(3)
	v_perm_b32 v13, v13, v12, s17
	s_waitcnt lgkmcnt(2)
	v_perm_b32 v12, v14, v11, s17
	v_perm_b32 v11, v10, v9, s17
	s_waitcnt lgkmcnt(0)
	v_perm_b32 v10, v16, v15, s17
	global_store_dwordx4 v[50:51], v[10:13], off
	v_lshl_add_u64 v[50:51], v[50:51], 0, s[68:69]
	s_barrier
	s_waitcnt vmcnt(7)
	ds_write_b128 v7, v[0:3]
	v_lshl_add_u64 v[48:49], v[48:49], 0, s[70:71]
	global_load_dwordx4 v[0:3], v[48:49], off
	s_waitcnt lgkmcnt(0)
	s_barrier
	ds_read_u16 v9, v8 offset:288
	ds_read_u16 v10, v8 offset:432
	ds_read_u16 v11, v8 offset:576
	ds_read_u16 v12, v8 offset:864
	ds_read_u16 v13, v8 offset:1008
	ds_read_u16 v14, v8 offset:720
	ds_read_u16 v15, v8
	ds_read_u16 v16, v8 offset:144
	s_waitcnt lgkmcnt(3)
	v_perm_b32 v13, v13, v12, s17
	s_waitcnt lgkmcnt(2)
	v_perm_b32 v12, v14, v11, s17
	v_perm_b32 v11, v10, v9, s17
	s_waitcnt lgkmcnt(0)
	v_perm_b32 v10, v16, v15, s17
	global_store_dwordx4 v[50:51], v[10:13], off
	v_lshl_add_u64 v[50:51], v[50:51], 0, s[68:69]
	s_barrier
	s_waitcnt vmcnt(7)
	ds_write_b128 v7, v[32:35]
	v_lshl_add_u64 v[48:49], v[48:49], 0, s[70:71]
	global_load_dwordx4 v[32:35], v[48:49], off
	s_waitcnt lgkmcnt(0)
	s_barrier
	ds_read_u16 v9, v8 offset:288
	ds_read_u16 v10, v8 offset:432
	ds_read_u16 v11, v8 offset:576
	ds_read_u16 v12, v8 offset:864
	ds_read_u16 v13, v8 offset:1008
	ds_read_u16 v14, v8 offset:720
	ds_read_u16 v15, v8
	ds_read_u16 v16, v8 offset:144
	s_waitcnt lgkmcnt(3)
	v_perm_b32 v13, v13, v12, s17
	s_waitcnt lgkmcnt(2)
	v_perm_b32 v12, v14, v11, s17
	v_perm_b32 v11, v10, v9, s17
	s_waitcnt lgkmcnt(0)
	v_perm_b32 v10, v16, v15, s17
	global_store_dwordx4 v[50:51], v[10:13], off
	v_lshl_add_u64 v[50:51], v[50:51], 0, s[68:69]
	s_barrier
	s_waitcnt vmcnt(7)
	ds_write_b128 v7, v[36:39]
	v_lshl_add_u64 v[48:49], v[48:49], 0, s[70:71]
	global_load_dwordx4 v[36:39], v[48:49], off
	s_waitcnt lgkmcnt(0)
	s_barrier
	ds_read_u16 v9, v8 offset:288
	ds_read_u16 v10, v8 offset:432
	ds_read_u16 v11, v8 offset:576
	ds_read_u16 v12, v8 offset:864
	ds_read_u16 v13, v8 offset:1008
	ds_read_u16 v14, v8 offset:720
	ds_read_u16 v15, v8
	ds_read_u16 v16, v8 offset:144
	s_waitcnt lgkmcnt(3)
	v_perm_b32 v13, v13, v12, s17
	s_waitcnt lgkmcnt(2)
	v_perm_b32 v12, v14, v11, s17
	v_perm_b32 v11, v10, v9, s17
	s_waitcnt lgkmcnt(0)
	v_perm_b32 v10, v16, v15, s17
	global_store_dwordx4 v[50:51], v[10:13], off
	v_lshl_add_u64 v[50:51], v[50:51], 0, s[68:69]
	s_barrier
	s_waitcnt vmcnt(7)
	ds_write_b128 v7, v[40:43]
	v_lshl_add_u64 v[48:49], v[48:49], 0, s[70:71]
	global_load_dwordx4 v[40:43], v[48:49], off
	s_waitcnt lgkmcnt(0)
	s_barrier
	ds_read_u16 v9, v8 offset:288
	ds_read_u16 v10, v8 offset:432
	ds_read_u16 v11, v8 offset:576
	ds_read_u16 v12, v8 offset:864
	ds_read_u16 v13, v8 offset:1008
	ds_read_u16 v14, v8 offset:720
	ds_read_u16 v15, v8
	ds_read_u16 v16, v8 offset:144
	s_waitcnt lgkmcnt(3)
	v_perm_b32 v13, v13, v12, s17
	s_waitcnt lgkmcnt(2)
	v_perm_b32 v12, v14, v11, s17
	v_perm_b32 v11, v10, v9, s17
	s_waitcnt lgkmcnt(0)
	v_perm_b32 v10, v16, v15, s17
	global_store_dwordx4 v[50:51], v[10:13], off
	v_lshl_add_u64 v[50:51], v[50:51], 0, s[68:69]
	s_barrier
	s_waitcnt vmcnt(7)
	ds_write_b128 v7, v[0:3]
	v_lshl_add_u64 v[48:49], v[48:49], 0, s[70:71]
	global_load_dwordx4 v[0:3], v[48:49], off
	s_waitcnt lgkmcnt(0)
	s_barrier
	ds_read_u16 v9, v8 offset:288
	ds_read_u16 v10, v8 offset:432
	ds_read_u16 v11, v8 offset:576
	ds_read_u16 v12, v8 offset:864
	ds_read_u16 v13, v8 offset:1008
	ds_read_u16 v14, v8 offset:720
	ds_read_u16 v15, v8
	ds_read_u16 v16, v8 offset:144
	s_waitcnt lgkmcnt(3)
	v_perm_b32 v13, v13, v12, s17
	s_waitcnt lgkmcnt(2)
	v_perm_b32 v12, v14, v11, s17
	v_perm_b32 v11, v10, v9, s17
	s_waitcnt lgkmcnt(0)
	v_perm_b32 v10, v16, v15, s17
	global_store_dwordx4 v[50:51], v[10:13], off
	v_lshl_add_u64 v[50:51], v[50:51], 0, s[68:69]
	s_barrier
	s_waitcnt vmcnt(7)
	ds_write_b128 v7, v[32:35]
	v_lshl_add_u64 v[48:49], v[48:49], 0, s[70:71]
	global_load_dwordx4 v[32:35], v[48:49], off
	s_waitcnt lgkmcnt(0)
	s_barrier
	ds_read_u16 v9, v8 offset:288
	ds_read_u16 v10, v8 offset:432
	ds_read_u16 v11, v8 offset:576
	ds_read_u16 v12, v8 offset:864
	ds_read_u16 v13, v8 offset:1008
	ds_read_u16 v14, v8 offset:720
	ds_read_u16 v15, v8
	ds_read_u16 v16, v8 offset:144
	s_waitcnt lgkmcnt(3)
	v_perm_b32 v13, v13, v12, s17
	s_waitcnt lgkmcnt(2)
	v_perm_b32 v12, v14, v11, s17
	v_perm_b32 v11, v10, v9, s17
	s_waitcnt lgkmcnt(0)
	v_perm_b32 v10, v16, v15, s17
	global_store_dwordx4 v[50:51], v[10:13], off
	v_lshl_add_u64 v[50:51], v[50:51], 0, s[68:69]
	s_barrier
	s_waitcnt vmcnt(7)
	ds_write_b128 v7, v[36:39]
	v_lshl_add_u64 v[48:49], v[48:49], 0, s[70:71]
	global_load_dwordx4 v[36:39], v[48:49], off
	s_waitcnt lgkmcnt(0)
	s_barrier
	ds_read_u16 v9, v8 offset:288
	ds_read_u16 v10, v8 offset:432
	ds_read_u16 v11, v8 offset:576
	ds_read_u16 v12, v8 offset:864
	ds_read_u16 v13, v8 offset:1008
	ds_read_u16 v14, v8 offset:720
	ds_read_u16 v15, v8
	ds_read_u16 v16, v8 offset:144
	s_waitcnt lgkmcnt(3)
	v_perm_b32 v13, v13, v12, s17
	s_waitcnt lgkmcnt(2)
	v_perm_b32 v12, v14, v11, s17
	v_perm_b32 v11, v10, v9, s17
	s_waitcnt lgkmcnt(0)
	v_perm_b32 v10, v16, v15, s17
	global_store_dwordx4 v[50:51], v[10:13], off
	v_lshl_add_u64 v[50:51], v[50:51], 0, s[68:69]
	s_barrier
	s_waitcnt vmcnt(7)
	ds_write_b128 v7, v[40:43]
	v_lshl_add_u64 v[48:49], v[48:49], 0, s[70:71]
	global_load_dwordx4 v[40:43], v[48:49], off
	s_waitcnt lgkmcnt(0)
	s_barrier
	ds_read_u16 v9, v8 offset:288
	ds_read_u16 v10, v8 offset:432
	ds_read_u16 v11, v8 offset:576
	ds_read_u16 v12, v8 offset:864
	ds_read_u16 v13, v8 offset:1008
	ds_read_u16 v14, v8 offset:720
	ds_read_u16 v15, v8
	ds_read_u16 v16, v8 offset:144
	s_waitcnt lgkmcnt(3)
	v_perm_b32 v13, v13, v12, s17
	s_waitcnt lgkmcnt(2)
	v_perm_b32 v12, v14, v11, s17
	v_perm_b32 v11, v10, v9, s17
	s_waitcnt lgkmcnt(0)
	v_perm_b32 v10, v16, v15, s17
	global_store_dwordx4 v[50:51], v[10:13], off
	v_lshl_add_u64 v[50:51], v[50:51], 0, s[68:69]
	s_barrier
	s_waitcnt vmcnt(7)
	ds_write_b128 v7, v[0:3]
	v_lshl_add_u64 v[48:49], v[48:49], 0, s[70:71]
	global_load_dwordx4 v[0:3], v[48:49], off
	s_waitcnt lgkmcnt(0)
	s_barrier
	ds_read_u16 v9, v8 offset:288
	ds_read_u16 v10, v8 offset:432
	ds_read_u16 v11, v8 offset:576
	ds_read_u16 v12, v8 offset:864
	ds_read_u16 v13, v8 offset:1008
	ds_read_u16 v14, v8 offset:720
	ds_read_u16 v15, v8
	ds_read_u16 v16, v8 offset:144
	s_waitcnt lgkmcnt(3)
	v_perm_b32 v13, v13, v12, s17
	s_waitcnt lgkmcnt(2)
	v_perm_b32 v12, v14, v11, s17
	v_perm_b32 v11, v10, v9, s17
	s_waitcnt lgkmcnt(0)
	v_perm_b32 v10, v16, v15, s17
	global_store_dwordx4 v[50:51], v[10:13], off
	v_lshl_add_u64 v[50:51], v[50:51], 0, s[68:69]
	s_barrier
	s_waitcnt vmcnt(7)
	ds_write_b128 v7, v[32:35]
	v_lshl_add_u64 v[48:49], v[48:49], 0, s[70:71]
	global_load_dwordx4 v[32:35], v[48:49], off
	s_waitcnt lgkmcnt(0)
	s_barrier
	ds_read_u16 v9, v8 offset:288
	ds_read_u16 v10, v8 offset:432
	ds_read_u16 v11, v8 offset:576
	ds_read_u16 v12, v8 offset:864
	ds_read_u16 v13, v8 offset:1008
	ds_read_u16 v14, v8 offset:720
	ds_read_u16 v15, v8
	ds_read_u16 v16, v8 offset:144
	s_waitcnt lgkmcnt(3)
	v_perm_b32 v13, v13, v12, s17
	s_waitcnt lgkmcnt(2)
	v_perm_b32 v12, v14, v11, s17
	v_perm_b32 v11, v10, v9, s17
	s_waitcnt lgkmcnt(0)
	v_perm_b32 v10, v16, v15, s17
	global_store_dwordx4 v[50:51], v[10:13], off
	v_lshl_add_u64 v[50:51], v[50:51], 0, s[68:69]
	s_barrier
	s_waitcnt vmcnt(7)
	ds_write_b128 v7, v[36:39]
	v_lshl_add_u64 v[48:49], v[48:49], 0, s[70:71]
	global_load_dwordx4 v[36:39], v[48:49], off
	s_waitcnt lgkmcnt(0)
	s_barrier
	ds_read_u16 v9, v8 offset:288
	ds_read_u16 v10, v8 offset:432
	ds_read_u16 v11, v8 offset:576
	ds_read_u16 v12, v8 offset:864
	ds_read_u16 v13, v8 offset:1008
	ds_read_u16 v14, v8 offset:720
	ds_read_u16 v15, v8
	ds_read_u16 v16, v8 offset:144
	s_waitcnt lgkmcnt(3)
	v_perm_b32 v13, v13, v12, s17
	s_waitcnt lgkmcnt(2)
	v_perm_b32 v12, v14, v11, s17
	v_perm_b32 v11, v10, v9, s17
	s_waitcnt lgkmcnt(0)
	v_perm_b32 v10, v16, v15, s17
	global_store_dwordx4 v[50:51], v[10:13], off
	v_lshl_add_u64 v[50:51], v[50:51], 0, s[68:69]
	s_barrier
	s_waitcnt vmcnt(7)
	ds_write_b128 v7, v[40:43]
	v_lshl_add_u64 v[48:49], v[48:49], 0, s[70:71]
	global_load_dwordx4 v[40:43], v[48:49], off
	s_waitcnt lgkmcnt(0)
	s_barrier
	ds_read_u16 v9, v8 offset:288
	ds_read_u16 v10, v8 offset:432
	ds_read_u16 v11, v8 offset:576
	ds_read_u16 v12, v8 offset:864
	ds_read_u16 v13, v8 offset:1008
	ds_read_u16 v14, v8 offset:720
	ds_read_u16 v15, v8
	ds_read_u16 v16, v8 offset:144
	s_waitcnt lgkmcnt(3)
	v_perm_b32 v13, v13, v12, s17
	s_waitcnt lgkmcnt(2)
	v_perm_b32 v12, v14, v11, s17
	v_perm_b32 v11, v10, v9, s17
	s_waitcnt lgkmcnt(0)
	v_perm_b32 v10, v16, v15, s17
	global_store_dwordx4 v[50:51], v[10:13], off
	v_lshl_add_u64 v[50:51], v[50:51], 0, s[68:69]
	s_barrier
	s_waitcnt vmcnt(7)
	ds_write_b128 v7, v[0:3]
	v_lshl_add_u64 v[48:49], v[48:49], 0, s[70:71]
	global_load_dwordx4 v[0:3], v[48:49], off
	s_waitcnt lgkmcnt(0)
	s_barrier
	ds_read_u16 v9, v8 offset:288
	ds_read_u16 v10, v8 offset:432
	ds_read_u16 v11, v8 offset:576
	ds_read_u16 v12, v8 offset:864
	ds_read_u16 v13, v8 offset:1008
	ds_read_u16 v14, v8 offset:720
	ds_read_u16 v15, v8
	ds_read_u16 v16, v8 offset:144
	s_waitcnt lgkmcnt(3)
	v_perm_b32 v13, v13, v12, s17
	s_waitcnt lgkmcnt(2)
	v_perm_b32 v12, v14, v11, s17
	v_perm_b32 v11, v10, v9, s17
	s_waitcnt lgkmcnt(0)
	v_perm_b32 v10, v16, v15, s17
	global_store_dwordx4 v[50:51], v[10:13], off
	v_lshl_add_u64 v[50:51], v[50:51], 0, s[68:69]
	s_barrier
	s_waitcnt vmcnt(7)
	ds_write_b128 v7, v[32:35]
	v_lshl_add_u64 v[48:49], v[48:49], 0, s[70:71]
	global_load_dwordx4 v[32:35], v[48:49], off
	s_waitcnt lgkmcnt(0)
	s_barrier
	ds_read_u16 v9, v8 offset:288
	ds_read_u16 v10, v8 offset:432
	ds_read_u16 v11, v8 offset:576
	ds_read_u16 v12, v8 offset:864
	ds_read_u16 v13, v8 offset:1008
	ds_read_u16 v14, v8 offset:720
	ds_read_u16 v15, v8
	ds_read_u16 v16, v8 offset:144
	s_waitcnt lgkmcnt(3)
	v_perm_b32 v13, v13, v12, s17
	s_waitcnt lgkmcnt(2)
	v_perm_b32 v12, v14, v11, s17
	v_perm_b32 v11, v10, v9, s17
	s_waitcnt lgkmcnt(0)
	v_perm_b32 v10, v16, v15, s17
	global_store_dwordx4 v[50:51], v[10:13], off
	v_lshl_add_u64 v[50:51], v[50:51], 0, s[68:69]
	s_barrier
	s_waitcnt vmcnt(7)
	ds_write_b128 v7, v[36:39]
	v_lshl_add_u64 v[48:49], v[48:49], 0, s[70:71]
	global_load_dwordx4 v[36:39], v[48:49], off
	s_waitcnt lgkmcnt(0)
	s_barrier
	ds_read_u16 v9, v8 offset:288
	ds_read_u16 v10, v8 offset:432
	ds_read_u16 v11, v8 offset:576
	ds_read_u16 v12, v8 offset:864
	ds_read_u16 v13, v8 offset:1008
	ds_read_u16 v14, v8 offset:720
	ds_read_u16 v15, v8
	ds_read_u16 v16, v8 offset:144
	s_waitcnt lgkmcnt(3)
	v_perm_b32 v13, v13, v12, s17
	s_waitcnt lgkmcnt(2)
	v_perm_b32 v12, v14, v11, s17
	v_perm_b32 v11, v10, v9, s17
	s_waitcnt lgkmcnt(0)
	v_perm_b32 v10, v16, v15, s17
	global_store_dwordx4 v[50:51], v[10:13], off
	v_lshl_add_u64 v[50:51], v[50:51], 0, s[68:69]
	s_barrier
	s_waitcnt vmcnt(7)
	ds_write_b128 v7, v[40:43]
	v_lshl_add_u64 v[48:49], v[48:49], 0, s[70:71]
	global_load_dwordx4 v[40:43], v[48:49], off
	s_waitcnt lgkmcnt(0)
	s_barrier
	ds_read_u16 v9, v8 offset:288
	ds_read_u16 v10, v8 offset:432
	ds_read_u16 v11, v8 offset:576
	ds_read_u16 v12, v8 offset:864
	ds_read_u16 v13, v8 offset:1008
	ds_read_u16 v14, v8 offset:720
	ds_read_u16 v15, v8
	ds_read_u16 v16, v8 offset:144
	s_waitcnt lgkmcnt(3)
	v_perm_b32 v13, v13, v12, s17
	s_waitcnt lgkmcnt(2)
	v_perm_b32 v12, v14, v11, s17
	v_perm_b32 v11, v10, v9, s17
	s_waitcnt lgkmcnt(0)
	v_perm_b32 v10, v16, v15, s17
	global_store_dwordx4 v[50:51], v[10:13], off
	v_lshl_add_u64 v[50:51], v[50:51], 0, s[68:69]
	s_barrier
	s_waitcnt vmcnt(7)
	ds_write_b128 v7, v[0:3]
	v_lshl_add_u64 v[48:49], v[48:49], 0, s[70:71]
	global_load_dwordx4 v[0:3], v[48:49], off
	s_waitcnt lgkmcnt(0)
	s_barrier
	ds_read_u16 v9, v8 offset:288
	ds_read_u16 v10, v8 offset:432
	ds_read_u16 v11, v8 offset:576
	ds_read_u16 v12, v8 offset:864
	ds_read_u16 v13, v8 offset:1008
	ds_read_u16 v14, v8 offset:720
	ds_read_u16 v15, v8
	ds_read_u16 v16, v8 offset:144
	s_waitcnt lgkmcnt(3)
	v_perm_b32 v13, v13, v12, s17
	s_waitcnt lgkmcnt(2)
	v_perm_b32 v12, v14, v11, s17
	v_perm_b32 v11, v10, v9, s17
	s_waitcnt lgkmcnt(0)
	v_perm_b32 v10, v16, v15, s17
	global_store_dwordx4 v[50:51], v[10:13], off
	v_lshl_add_u64 v[50:51], v[50:51], 0, s[68:69]
	s_barrier
	s_waitcnt vmcnt(7)
	ds_write_b128 v7, v[32:35]
	v_lshl_add_u64 v[48:49], v[48:49], 0, s[70:71]
	global_load_dwordx4 v[32:35], v[48:49], off
	s_waitcnt lgkmcnt(0)
	s_barrier
	ds_read_u16 v9, v8 offset:288
	ds_read_u16 v10, v8 offset:432
	ds_read_u16 v11, v8 offset:576
	ds_read_u16 v12, v8 offset:864
	ds_read_u16 v13, v8 offset:1008
	ds_read_u16 v14, v8 offset:720
	ds_read_u16 v15, v8
	ds_read_u16 v16, v8 offset:144
	s_waitcnt lgkmcnt(3)
	v_perm_b32 v13, v13, v12, s17
	s_waitcnt lgkmcnt(2)
	v_perm_b32 v12, v14, v11, s17
	v_perm_b32 v11, v10, v9, s17
	s_waitcnt lgkmcnt(0)
	v_perm_b32 v10, v16, v15, s17
	global_store_dwordx4 v[50:51], v[10:13], off
	v_lshl_add_u64 v[50:51], v[50:51], 0, s[68:69]
	s_barrier
	s_waitcnt vmcnt(7)
	ds_write_b128 v7, v[36:39]
	v_lshl_add_u64 v[48:49], v[48:49], 0, s[70:71]
	global_load_dwordx4 v[36:39], v[48:49], off
	s_waitcnt lgkmcnt(0)
	s_barrier
	ds_read_u16 v9, v8 offset:288
	ds_read_u16 v10, v8 offset:432
	ds_read_u16 v11, v8 offset:576
	ds_read_u16 v12, v8 offset:864
	ds_read_u16 v13, v8 offset:1008
	ds_read_u16 v14, v8 offset:720
	ds_read_u16 v15, v8
	ds_read_u16 v16, v8 offset:144
	s_waitcnt lgkmcnt(3)
	v_perm_b32 v13, v13, v12, s17
	s_waitcnt lgkmcnt(2)
	v_perm_b32 v12, v14, v11, s17
	v_perm_b32 v11, v10, v9, s17
	s_waitcnt lgkmcnt(0)
	v_perm_b32 v10, v16, v15, s17
	global_store_dwordx4 v[50:51], v[10:13], off
	v_lshl_add_u64 v[50:51], v[50:51], 0, s[68:69]
	s_barrier
	s_waitcnt vmcnt(7)
	ds_write_b128 v7, v[40:43]
	v_lshl_add_u64 v[48:49], v[48:49], 0, s[70:71]
	global_load_dwordx4 v[40:43], v[48:49], off
	s_waitcnt lgkmcnt(0)
	s_barrier
	ds_read_u16 v9, v8 offset:288
	ds_read_u16 v10, v8 offset:432
	ds_read_u16 v11, v8 offset:576
	ds_read_u16 v12, v8 offset:864
	ds_read_u16 v13, v8 offset:1008
	ds_read_u16 v14, v8 offset:720
	ds_read_u16 v15, v8
	ds_read_u16 v16, v8 offset:144
	s_waitcnt lgkmcnt(3)
	v_perm_b32 v13, v13, v12, s17
	s_waitcnt lgkmcnt(2)
	v_perm_b32 v12, v14, v11, s17
	v_perm_b32 v11, v10, v9, s17
	s_waitcnt lgkmcnt(0)
	v_perm_b32 v10, v16, v15, s17
	global_store_dwordx4 v[50:51], v[10:13], off
	v_lshl_add_u64 v[50:51], v[50:51], 0, s[68:69]
	s_barrier
	s_waitcnt vmcnt(7)
	ds_write_b128 v7, v[0:3]
	s_waitcnt lgkmcnt(0)
	s_barrier
	ds_read_u16 v9, v8 offset:288
	ds_read_u16 v10, v8 offset:432
	ds_read_u16 v11, v8 offset:576
	ds_read_u16 v12, v8 offset:864
	ds_read_u16 v13, v8 offset:1008
	ds_read_u16 v14, v8 offset:720
	ds_read_u16 v15, v8
	ds_read_u16 v16, v8 offset:144
	s_waitcnt lgkmcnt(3)
	v_perm_b32 v13, v13, v12, s17
	s_waitcnt lgkmcnt(2)
	v_perm_b32 v12, v14, v11, s17
	v_perm_b32 v11, v10, v9, s17
	s_waitcnt lgkmcnt(0)
	v_perm_b32 v10, v16, v15, s17
	global_store_dwordx4 v[50:51], v[10:13], off
	v_lshl_add_u64 v[50:51], v[50:51], 0, s[68:69]
	s_barrier
	s_waitcnt vmcnt(6)
	ds_write_b128 v7, v[32:35]
	s_waitcnt lgkmcnt(0)
	s_barrier
	ds_read_u16 v9, v8 offset:288
	ds_read_u16 v10, v8 offset:432
	ds_read_u16 v11, v8 offset:576
	ds_read_u16 v12, v8 offset:864
	ds_read_u16 v13, v8 offset:1008
	ds_read_u16 v14, v8 offset:720
	ds_read_u16 v15, v8
	ds_read_u16 v16, v8 offset:144
	s_waitcnt lgkmcnt(3)
	v_perm_b32 v13, v13, v12, s17
	s_waitcnt lgkmcnt(2)
	v_perm_b32 v12, v14, v11, s17
	v_perm_b32 v11, v10, v9, s17
	s_waitcnt lgkmcnt(0)
	v_perm_b32 v10, v16, v15, s17
	global_store_dwordx4 v[50:51], v[10:13], off
	v_lshl_add_u64 v[50:51], v[50:51], 0, s[68:69]
	s_barrier
	s_waitcnt vmcnt(5)
	ds_write_b128 v7, v[36:39]
	s_waitcnt lgkmcnt(0)
	s_barrier
	ds_read_u16 v9, v8 offset:288
	ds_read_u16 v10, v8 offset:432
	ds_read_u16 v11, v8 offset:576
	ds_read_u16 v12, v8 offset:864
	ds_read_u16 v13, v8 offset:1008
	ds_read_u16 v14, v8 offset:720
	ds_read_u16 v15, v8
	ds_read_u16 v16, v8 offset:144
	s_waitcnt lgkmcnt(3)
	v_perm_b32 v13, v13, v12, s17
	s_waitcnt lgkmcnt(2)
	v_perm_b32 v12, v14, v11, s17
	v_perm_b32 v11, v10, v9, s17
	s_waitcnt lgkmcnt(0)
	v_perm_b32 v10, v16, v15, s17
	global_store_dwordx4 v[50:51], v[10:13], off
	v_lshl_add_u64 v[50:51], v[50:51], 0, s[68:69]
	s_barrier
	s_waitcnt vmcnt(4)
	ds_write_b128 v7, v[40:43]
	s_waitcnt lgkmcnt(0)
	s_barrier
	ds_read_u16 v9, v8 offset:288
	ds_read_u16 v10, v8 offset:432
	ds_read_u16 v11, v8 offset:576
	ds_read_u16 v12, v8 offset:864
	ds_read_u16 v13, v8 offset:1008
	ds_read_u16 v14, v8 offset:720
	ds_read_u16 v15, v8
	ds_read_u16 v16, v8 offset:144
	s_waitcnt lgkmcnt(3)
	v_perm_b32 v13, v13, v12, s17
	s_waitcnt lgkmcnt(2)
	v_perm_b32 v12, v14, v11, s17
	v_perm_b32 v11, v10, v9, s17
	s_waitcnt lgkmcnt(0)
	v_perm_b32 v10, v16, v15, s17
	global_store_dwordx4 v[50:51], v[10:13], off
	v_lshl_add_u64 v[50:51], v[50:51], 0, s[68:69]
	s_barrier
	s_branch .LBB0_2136
